# attention K/V tile loads use SGPR running base plus loop-invariant 32-bit VGPR offsets (no per-iteration 64-bit VALU address math)
# speedup vs baseline: 1.0030x; 1.0030x over previous
; #define AT_LOAD(t) do { _Pragma("unroll") for (int i = 0; i < 2; ++i) { const int p = tid + 512 * i; \
;             kr[i] = *(const u32x4*)(kbase + (size_t)((t) * 64 + (p >> 4)) * HP1 + (p & 15) * 8); \
;             vr[i] = *(const u32x4*)(vbase + (size_t)(p >> 3) * R + (t) * 64 + (p & 7) * 8); } } while (0)
; #define AT_STORE(bo) do { _Pragma("unroll") for (int i = 0; i < 2; ++i) { const int p = tid + 512 * i; const int part = p & 15; \
;             *(LAS u32x4*)(lds + (bo) + (part >> 3) * AT_K2 + (p >> 4) * AT_KS + (part & 7) * 16) = kr[i]; \
;             *(LAS u32x4*)(lds + (bo) + AT_V + (p >> 3) * AT_KS + (p & 7) * 16) = vr[i]; } } while (0)
; #define AT_NOP() asm volatile("s_nop 7\n\ts_nop 7" ::: "memory")
; #define AT_RD4(d0, d1, d2, d3, addr, o0, o1, o2, o3) do { DSR(d0, addr, o0); DSR(d1, addr, o1); DSR(d2, addr, o2); DSR(d3, addr, o3); } while (0)
; __device__ __forceinline__ void attn_phase(KA a, lds8* lds, int tid, int lane, int wave) {
;     ...
;         const int q0 = seqb + 128 * qb; const int myrow = q0 + 32 * qg + l31;
;         bf16x8 qf[4];
; #pragma unroll
;         for (int ks = 0; ks < 4; ++ks) qf[ks] = *(const bf16x8*)(H + (size_t)myrow * HP1 + 1024 + h * 128 + map * 64 + 16 * ks + 8 * hh);
;         f32x16 O[4], negm = zero16;
; #pragma unroll
;         for (int db = 0; db < 4; ++db) O[db] = zero16;
;         float lsA = 0.f, lsB = 0.f, lsC = 0.f, lsD = 0.f;
;         const int nt = S / 64;
;         u32x4 kr[2], vr[2];
;         const bf16_t* kbase = H + (size_t)seqb * HP1 + 2048 + h * 128; const bf16_t* vbase = VT + (size_t)(h * 128) * R + seqb;
;     ...
;         bf16x8 pf[2][2]; bf16x8 kf[4], vf[8];
;         const unsigned lds0 = (unsigned)(size_t)lds;
;         const unsigned kaddr0 = lds0 + map * AT_K2 + krow_off, vaddr0 = lds0 + AT_V + vrow_off;
;         __syncthreads();
;         AT_LOAD(0); AT_STORE(0);
;         __syncthreads();
;         int bcur = 0, bprev = 2 * AT_BUF;
;         for (int t = 0; t < nt; ++t) {
;             const int bnext = bcur == 2 * AT_BUF ? 0 : bcur + AT_BUF;
;             if (t + 1 < nt) AT_LOAD(t + 1);
;             if (map == 1 && t > 0) { AT_PVRD(vaddr0 + bprev); AT_PVMM(vaddr0 + bprev); AT_NOP(); }
;             AT_RD4(kf[0], kf[1], kf[2], kf[3], kaddr0 + bcur, 0, 32, 64, 96); AT_RD4(vf[0], vf[1], vf[2], vf[3], kaddr0 + bcur, 4608, 4640, 4672, 4704);
.LBB0_1303:
	s_lshl_b32 s8, s15, 7
	s_add_i32 s8, s18, s8
	s_lshl_b32 s52, s14, 7
	v_or_b32_e32 v180, s8, v245
	v_mov_b64_e32 v[0:1], s[16:17]
	s_ashr_i32 s53, s52, 31
	v_mad_u64_u32 v[0:1], s[8:9], v180, s33, v[0:1]
	s_lshl_b64 s[12:13], s[52:53], 1
	s_mul_i32 s61, s18, 0x1800
	s_mul_hi_u32 s37, s18, 0x1800
	s_add_u32 s8, s16, s61
	s_addc_u32 s9, s17, s37
	s_add_u32 s8, s8, s12
	v_lshl_add_u64 v[0:1], v[0:1], 0, s[12:13]
	s_addc_u32 s9, s9, s13
	s_mul_i32 s62, s14, 0xc00000
	v_lshl_add_u64 v[0:1], v[0:1], 0, s[26:27]
	s_mul_hi_i32 s63, s52, 0x18000
	s_add_u32 s14, s10, s62
	v_lshl_add_u64 v[0:1], v[178:179], 1, v[0:1]
	s_addc_u32 s15, s11, s63
	s_lshl_b64 s[54:55], s[18:19], 1
	v_mov_b32_e32 v205, v181
	global_load_dwordx4 v[128:131], v[0:1], off offset:2048
	global_load_dwordx4 v[132:135], v[0:1], off offset:2080
	global_load_dwordx4 v[136:139], v[0:1], off offset:2112
	global_load_dwordx4 v[140:143], v[0:1], off offset:2144
	s_add_u32 s14, s14, s54
	v_lshl_add_u64 v[0:1], s[8:9], 0, v[204:205]
	s_addc_u32 s15, s15, s55
	v_lshl_add_u64 v[0:1], v[0:1], 0, s[28:29]
	v_mov_b32_e32 v207, v181
	v_lshl_add_u64 v[2:3], s[14:15], 0, v[206:207]
	v_lshl_add_u64 v[4:5], v[0:1], 0, v[184:185]
	v_lshl_add_u64 v[0:1], v[0:1], 0, v[188:189]
	s_barrier
	v_lshl_add_u64 v[6:7], v[2:3], 0, v[186:187]
	global_load_dwordx4 v[144:147], v[4:5], off
	global_load_dwordx4 v[148:151], v[6:7], off
	v_lshl_add_u64 v[2:3], v[2:3], 0, v[190:191]
	global_load_dwordx4 v[152:155], v[0:1], off
	global_load_dwordx4 v[156:159], v[2:3], off
	s_add_u32 s8, s12, s61
	s_addc_u32 s9, s13, s37
	s_add_u32 s98, s8, s24
	s_addc_u32 s99, s9, s25
	v_mov_b32_e32 v14, v181
	v_mov_b32_e32 v15, v181
	v_lshl_add_u64 v[212:213], s[8:9], 0, v[196:197]
	v_lshl_add_u64 v[214:215], s[8:9], 0, v[198:199]
	s_add_u32 s8, s54, s62
	v_mov_b32_e32 v208, v181
	v_mov_b32_e32 v209, v181
	v_mov_b32_e32 v0, v181
	v_mov_b32_e32 v1, v181
	v_mov_b32_e32 v2, v181
	v_mov_b32_e32 v3, v181
	v_mov_b32_e32 v4, v181
	v_mov_b32_e32 v5, v181
	v_mov_b32_e32 v6, v181
	v_mov_b32_e32 v7, v181
	v_mov_b32_e32 v8, v181
	v_mov_b32_e32 v9, v181
	v_mov_b32_e32 v10, v181
	v_mov_b32_e32 v11, v181
	v_mov_b32_e32 v12, v181
	v_mov_b32_e32 v13, v181
	v_mov_b64_e32 v[30:31], v[14:15]
	v_mov_b64_e32 v[46:47], v[14:15]
	v_mov_b64_e32 v[62:63], v[14:15]
	v_mov_b64_e32 v[78:79], v[14:15]
	s_addc_u32 s9, s55, s63
	s_add_u32 s100, s8, s24
	s_addc_u32 s101, s9, s25
	v_add_u32_e32 v96, v237, v238
	s_mov_b32 s14, 0x12000
	s_mov_b32 s15, 0
	s_mov_b32 s18, 0
	v_mov_b64_e32 v[28:29], v[12:13]
	v_mov_b64_e32 v[26:27], v[10:11]
	v_mov_b64_e32 v[24:25], v[8:9]
	v_mov_b64_e32 v[22:23], v[6:7]
	v_mov_b64_e32 v[20:21], v[4:5]
	v_mov_b64_e32 v[18:19], v[2:3]
	v_mov_b64_e32 v[16:17], v[0:1]
	v_mov_b64_e32 v[44:45], v[12:13]
	v_mov_b64_e32 v[42:43], v[10:11]
	v_mov_b64_e32 v[40:41], v[8:9]
	v_mov_b64_e32 v[38:39], v[6:7]
	v_mov_b64_e32 v[36:37], v[4:5]
	v_mov_b64_e32 v[34:35], v[2:3]
	v_mov_b64_e32 v[32:33], v[0:1]
	v_mov_b64_e32 v[60:61], v[12:13]
	v_mov_b64_e32 v[58:59], v[10:11]
	v_mov_b64_e32 v[56:57], v[8:9]
	v_mov_b64_e32 v[54:55], v[6:7]
	v_mov_b64_e32 v[52:53], v[4:5]
	v_mov_b64_e32 v[50:51], v[2:3]
	v_mov_b64_e32 v[48:49], v[0:1]
	v_mov_b64_e32 v[76:77], v[12:13]
	v_mov_b64_e32 v[74:75], v[10:11]
	v_mov_b64_e32 v[72:73], v[8:9]
	v_mov_b64_e32 v[70:71], v[6:7]
	v_mov_b64_e32 v[68:69], v[4:5]
	v_mov_b64_e32 v[66:67], v[2:3]
	v_mov_b64_e32 v[64:65], v[0:1]
	v_lshl_add_u64 v[216:217], s[8:9], 0, v[200:201]
	v_lshl_add_u64 v[218:219], s[8:9], 0, v[202:203]
	v_mov_b64_e32 v[210:211], v[208:209]
	v_add_u32_e32 v97, v236, v239
	v_add_u32_e32 v98, v237, v240
	v_add_u32_e32 v99, v236, v241
	s_waitcnt vmcnt(3)
	ds_write_b128 v96, v[144:147]
	s_waitcnt vmcnt(2)
	ds_write_b128 v97, v[148:151] offset:18432
	s_waitcnt vmcnt(1)
	ds_write_b128 v98, v[152:155]
	s_waitcnt vmcnt(0)
	ds_write_b128 v99, v[156:159] offset:18432
	global_load_dwordx4 v[144:147], v198, s[98:99]
	global_load_dwordx4 v[148:151], v202, s[100:101]
	global_load_dwordx4 v[152:155], v196, s[98:99]
	global_load_dwordx4 v[156:159], v200, s[100:101]
	s_waitcnt lgkmcnt(0)
	s_barrier

; #define AT_STORE(bo) do { _Pragma("unroll") for (int i = 0; i < 2; ++i) { const int p = tid + 512 * i; const int part = p & 15; \
;             *(LAS u32x4*)(lds + (bo) + (part >> 3) * AT_K2 + (p >> 4) * AT_KS + (part & 7) * 16) = kr[i]; \
;             *(LAS u32x4*)(lds + (bo) + AT_V + (p >> 3) * AT_KS + (p & 7) * 16) = vr[i]; } } while (0)
; __device__ __forceinline__ void attn_phase(KA a, lds8* lds, int tid, int lane, int wave) {
;     ...
;             if (t + 1 < nt) AT_STORE(bnext);
;             __syncthreads();
;             bprev = bcur; bcur = bnext;
.LBB0_1316:
	s_add_i32 s8, s61, 1
	s_cmp_ge_u32 s8, s60
	s_cbranch_scc1 .Lat_ld_skip
	s_add_u32 s98, s98, 0x60000
	s_addc_u32 s99, s99, 0
	s_add_u32 s100, s100, 0x80
	s_addc_u32 s101, s101, 0
	global_load_dwordx4 v[144:147], v198, s[98:99]
	global_load_dwordx4 v[148:151], v202, s[100:101]
	global_load_dwordx4 v[152:155], v196, s[98:99]
	global_load_dwordx4 v[156:159], v200, s[100:101]

; __global__ void __launch_bounds__(512, 2) fwd_megakernel(Args args_unused) {
	.amdhsa_kernel _Z14fwd_megakernel4Args
		.amdhsa_group_segment_fixed_size 0
		.amdhsa_private_segment_fixed_size 0
		.amdhsa_kernarg_size 448
		.amdhsa_user_sgpr_count 2
		.amdhsa_user_sgpr_dispatch_ptr 0
		.amdhsa_user_sgpr_queue_ptr 0
		.amdhsa_user_sgpr_kernarg_segment_ptr 1
		.amdhsa_user_sgpr_dispatch_id 0
		.amdhsa_user_sgpr_kernarg_preload_length 0
		.amdhsa_user_sgpr_kernarg_preload_offset 0
		.amdhsa_user_sgpr_private_segment_size 0
		.amdhsa_uses_dynamic_stack 0
		.amdhsa_enable_private_segment 0
		.amdhsa_system_sgpr_workgroup_id_x 1
		.amdhsa_system_sgpr_workgroup_id_y 0
		.amdhsa_system_sgpr_workgroup_id_z 0
		.amdhsa_system_sgpr_workgroup_info 0
		.amdhsa_system_vgpr_workitem_id 2
		.amdhsa_next_free_vgpr 256
		.amdhsa_next_free_sgpr 102
		.amdhsa_accum_offset 256
		.amdhsa_reserve_vcc 1
		.amdhsa_float_round_mode_32 0
		.amdhsa_float_round_mode_16_64 0
		.amdhsa_float_denorm_mode_32 3
		.amdhsa_float_denorm_mode_16_64 3
		.amdhsa_dx10_clamp 1
		.amdhsa_ieee_mode 1
		.amdhsa_fp16_overflow 0
		.amdhsa_tg_split 0
		.amdhsa_exception_fp_ieee_invalid_op 0
		.amdhsa_exception_fp_denorm_src 0
		.amdhsa_exception_fp_ieee_div_zero 0
		.amdhsa_exception_fp_ieee_overflow 0
		.amdhsa_exception_fp_ieee_underflow 0
		.amdhsa_exception_fp_ieee_inexact 0
		.amdhsa_exception_int_div_zero 0
	.end_amdhsa_kernel

; __global__ void __launch_bounds__(512, 2) fwd_megakernel(Args args_unused) {
amdhsa.kernels:
  - .agpr_count:     0
    .args:
      - .offset:         0
        .size:           192
        .value_kind:     by_value
      - .offset:         192
        .size:           4
        .value_kind:     hidden_block_count_x
      - .offset:         196
        .size:           4
        .value_kind:     hidden_block_count_y
      - .offset:         200
        .size:           4
        .value_kind:     hidden_block_count_z
      - .offset:         204
        .size:           2
        .value_kind:     hidden_group_size_x
      - .offset:         206
        .size:           2
        .value_kind:     hidden_group_size_y
      - .offset:         208
        .size:           2
        .value_kind:     hidden_group_size_z
      - .offset:         210
        .size:           2
        .value_kind:     hidden_remainder_x
      - .offset:         212
        .size:           2
        .value_kind:     hidden_remainder_y
      - .offset:         214
        .size:           2
        .value_kind:     hidden_remainder_z
      - .offset:         232
        .size:           8
        .value_kind:     hidden_global_offset_x
      - .offset:         240
        .size:           8
        .value_kind:     hidden_global_offset_y
      - .offset:         248
        .size:           8
        .value_kind:     hidden_global_offset_z
      - .offset:         256
        .size:           2
        .value_kind:     hidden_grid_dims
      - .offset:         280
        .size:           8
        .value_kind:     hidden_multigrid_sync_arg
      - .offset:         312
        .size:           4
        .value_kind:     hidden_dynamic_lds_size
    .group_segment_fixed_size: 0
    .kernarg_segment_align: 8
    .kernarg_segment_size: 448
    .language:       OpenCL C
    .language_version:
      - 2
      - 0
    .max_flat_workgroup_size: 512
    .name:           _Z14fwd_megakernel4Args
    .private_segment_fixed_size: 0
    .sgpr_count:     108
    .sgpr_spill_count: 14
    .symbol:         _Z14fwd_megakernel4Args.kd
    .uniform_work_group_size: 1
    .uses_dynamic_stack: false
    .vgpr_count:     256
    .vgpr_spill_count: 0
    .wavefront_size: 64
